# early L1 invalidate at arrival + XCC-local rounds where the waiters watch the arrival counter (no release hop)
# baseline (speedup 1.0000x reference)
; __device__ __forceinline__ unsigned xb_ld(unsigned* p)              { return __hip_atomic_load(p, __ATOMIC_RELAXED, __HIP_MEMORY_SCOPE_AGENT); }
; __device__ __forceinline__ unsigned xb_add(unsigned* p, unsigned v) { return __hip_atomic_fetch_add(p, v, __ATOMIC_RELAXED, __HIP_MEMORY_SCOPE_AGENT); }
; #define XB_SPIN(cond, bar) do { unsigned _sp = 0; while (cond) { __builtin_amdgcn_s_sleep(1); \
;     if ((++_sp & 255u) == 0u) { if (xb_ld(&(bar)[XB_TMO])) break; if (_sp > XB_SPIN_CAP) { atomicAdd(&(bar)[XB_TMO], 1u); break; } } } } while (0)
; __device__ __forceinline__ void xcd_barrier(const XcdBarrier& b, const int tid) {
;     ...
;             __builtin_amdgcn_fence(__ATOMIC_RELEASE, "agent");
;             asm volatile("s_waitcnt vmcnt(0)" ::: "memory");
;             const unsigned og = xb_add(&bar[XB_TOP], 1u);
;             const unsigned tg = og / nx;
;             if (og + 1u == (tg + 1u) * nx) xb_add(&bar[XB_TOPGEN], 1u);
;             else XB_SPIN(xb_ld(&bar[XB_TOPGEN]) == tg, bar);
;             __builtin_amdgcn_fence(__ATOMIC_ACQUIRE, "agent");
;             xb_add(&bar[XB_XGEN(b.x)], 1u);
;             asm volatile("s_waitcnt vmcnt(0)" ::: "memory");
.Lxb_rel:
	v_readlane_b32 s4, v250, 11
	v_readlane_b32 s5, v250, 12
	v_mov_b32_e32 v4, 1
	s_nop 4
	global_atomic_add v1, v4, s[4:5]
	s_branch .LBB0_622
